# MLA: first two K-fragment LDS reads of each tile issued immediately after the barrier (ahead of prefetch address math)
# baseline (speedup 1.0000x reference)
.LBB0_1374:
	s_and_b32 s99, s27, 1
	s_mul_i32 s99, s99, 0x3400
	v_add_u32_e32 v124, s99, v175
	ds_read_b128 v[76:79], v124
	ds_read_b128 v[88:91], v124 offset:64
	s_cmp_lt_u32 s27, 31
	s_cselect_b32 s43, s42, s26
	s_lshl_b32 s98, s27, 6
	s_add_i32 s98, s98, s43
	s_addk_i32 s98, 0xffc0
	s_lshl_b32 s100, s98, 11
	s_mov_b32 s101, 0
	v_mul_u32_u24_e32 v202, s98, v206
	v_lshl_add_u64 v[72:73], v[204:205], 0, v[202:203]
	global_load_dwordx4 v[72:75], v[72:73], off
	s_and_saveexec_b64 s[0:1], s[6:7]
	s_cbranch_execz .LBB0_1376
	v_mul_u32_u24_e32 v202, s98, v207
	v_lshl_add_u64 v[28:29], v[208:209], 0, v[202:203]
	global_load_dwordx4 v[28:31], v[28:29], off
.LBB0_1376:
	s_or_b64 exec, exec, s[0:1]
	v_lshl_add_u64 v[232:233], v[216:217], 0, s[100:101]
	global_load_dwordx4 v[232:235], v[232:233], off offset:128
	s_and_b32 s0, s27, 1
	s_mul_i32 s1, s0, 0x3400
	s_waitcnt lgkmcnt(1)
	v_mfma_f32_16x16x32_bf16 v[92:95], v[76:79], v[20:23], v[218:221]
	ds_read_b128 v[96:99], v124 offset:3328
	ds_read_b128 v[100:103], v124 offset:128
	ds_read_b128 v[108:111], v124 offset:6656
	ds_read_b128 v[112:115], v124 offset:6720
	ds_read_b128 v[120:123], v124 offset:9984
	ds_read_b128 v[182:185], v124 offset:6784
	v_mfma_f32_16x16x32_bf16 v[76:79], v[76:79], v[24:27], v[222:225]
	s_mul_i32 s1, s0, 0x2800
	s_waitcnt lgkmcnt(5)
	v_mfma_f32_16x16x32_bf16 v[104:107], v[96:99], v[20:23], v[218:221]
	v_mfma_f32_16x16x32_bf16 v[96:99], v[96:99], v[24:27], v[222:225]
	s_waitcnt lgkmcnt(3)
	v_mfma_f32_16x16x32_bf16 v[116:119], v[108:111], v[20:23], v[218:221]
	v_mfma_f32_16x16x32_bf16 v[108:111], v[108:111], v[24:27], v[222:225]
	s_waitcnt lgkmcnt(1)
	v_mfma_f32_16x16x32_bf16 v[80:83], v[120:123], v[20:23], v[218:221]
	v_mfma_f32_16x16x32_bf16 v[84:87], v[120:123], v[24:27], v[222:225]
	v_mfma_f32_16x16x32_bf16 v[92:95], v[88:91], v[12:15], v[92:95]
	v_mfma_f32_16x16x32_bf16 v[76:79], v[88:91], v[16:19], v[76:79]
	ds_read_b128 v[88:91], v124 offset:3392
	ds_read_b128 v[120:123], v124 offset:3456
	s_waitcnt lgkmcnt(1)
	v_mfma_f32_16x16x32_bf16 v[104:107], v[88:91], v[12:15], v[104:107]
	v_mfma_f32_16x16x32_bf16 v[88:91], v[88:91], v[16:19], v[96:99]
	s_nop 2
	ds_read_b128 v[96:99], v124 offset:10048
	ds_read_b128 v[190:193], v124 offset:10112
	s_waitcnt lgkmcnt(1)
	v_mfma_f32_16x16x32_bf16 v[194:197], v[96:99], v[12:15], v[80:83]
	s_nop 2
	v_mfma_f32_16x16x32_bf16 v[128:131], v[100:103], v[4:7], v[76:79]
	v_add_u32_e32 v82, s1, v176
	s_nop 1
	v_mfma_f32_16x16x32_bf16 v[116:119], v[112:115], v[12:15], v[116:119]
	v_mfma_f32_16x16x32_bf16 v[186:189], v[112:115], v[16:19], v[108:111]
	v_mfma_f32_16x16x32_bf16 v[198:201], v[96:99], v[16:19], v[84:87]
	ds_read_b64_tr_b16 v[124:125], v82 offset:26624
	ds_read_b64_tr_b16 v[112:113], v82 offset:26656
	ds_read_b64_tr_b16 v[108:109], v82 offset:26688
	ds_read_b64_tr_b16 v[96:97], v82 offset:26720
	ds_read_b64_tr_b16 v[126:127], v82 offset:29184
	ds_read_b64_tr_b16 v[114:115], v82 offset:29216
	ds_read_b64_tr_b16 v[110:111], v82 offset:29248
	ds_read_b64_tr_b16 v[98:99], v82 offset:29280
	v_mfma_f32_16x16x32_bf16 v[136:139], v[100:103], v[8:11], v[92:95]
	v_mfma_f32_16x16x32_bf16 v[132:135], v[120:123], v[4:7], v[88:91]
	s_nop 1
	ds_read_b64_tr_b16 v[92:93], v82 offset:31744
	ds_read_b64_tr_b16 v[88:89], v82 offset:31776
	ds_read_b64_tr_b16 v[84:85], v82 offset:31808
	ds_read_b64_tr_b16 v[80:81], v82 offset:31840
	ds_read_b64_tr_b16 v[94:95], v82 offset:34304
	ds_read_b64_tr_b16 v[90:91], v82 offset:34336
	ds_read_b64_tr_b16 v[86:87], v82 offset:34368
	ds_read_b64_tr_b16 v[82:83], v82 offset:34400
	v_mfma_f32_16x16x32_bf16 v[140:143], v[120:123], v[8:11], v[104:107]
	v_mfma_f32_16x16x32_bf16 v[116:119], v[182:185], v[8:11], v[116:119]
	v_mfma_f32_16x16x32_bf16 v[100:103], v[182:185], v[4:7], v[186:189]
	s_waitcnt lgkmcnt(14)
	v_mfma_f32_16x16x32_bf16 v[120:123], v[190:193], v[8:11], v[194:197]
	v_mfma_f32_16x16x32_bf16 v[104:107], v[190:193], v[4:7], v[198:201]
	v_max3_f32 v181, v136, v137, v138
	v_max3_f32 v183, v128, v129, v130
	v_max3_f32 v184, v131, v132, v133
	v_max3_f32 v181, v181, v139, v140
	v_max3_f32 v183, v183, v134, v135
	v_max3_f32 v181, v181, v141, v142
	v_max3_f32 v182, v143, v116, v117
	v_max3_f32 v184, v184, v100, v101
	v_max3_f32 v182, v182, v118, v119
	v_max3_f32 v184, v184, v102, v103
	v_max3_f32 v181, v181, v120, v121
	v_max3_f32 v182, v182, v122, v123
	v_max3_f32 v183, v183, v104, v105
	v_max3_f32 v184, v184, v106, v107
	v_max_f32_e32 v181, v181, v182
	v_max_f32_e32 v183, v183, v184
	v_max_f32_e32 v184, v181, v183
	v_cmp_lt_f32_e32 vcc, s36, v184
	s_cbranch_vccz .LBB0_1378
	v_mov_b32_e32 v182, v181
	v_mov_b32_e32 v184, v183
	s_nop 1
	v_permlane16_swap_b32_e32 v181, v182
	v_permlane16_swap_b32_e32 v183, v184
	v_max_f32_e32 v181, v181, v182
	v_max_f32_e32 v183, v183, v184
	v_mov_b32_e32 v182, v181
	v_mov_b32_e32 v184, v183
	s_nop 1
	v_permlane32_swap_b32_e32 v181, v182
	v_permlane32_swap_b32_e32 v183, v184
	v_max_f32_e32 v182, v181, v182
	v_max_f32_e32 v181, v183, v184
	v_max_f32_e32 v182, v182, v182
	v_max_f32_e32 v183, 0, v182
	v_exp_f32_e64 v182, -v183
	v_max_f32_e32 v181, v181, v181
	v_sub_f32_e32 v136, v136, v183
	v_sub_f32_e32 v137, v137, v183
	v_pk_mul_f32 v[70:71], v[70:71], v[182:183] op_sel_hi:[1,0]
	v_pk_mul_f32 v[68:69], v[68:69], v[182:183] op_sel_hi:[1,0]
	v_pk_mul_f32 v[62:63], v[62:63], v[182:183] op_sel_hi:[1,0]
	v_pk_mul_f32 v[60:61], v[60:61], v[182:183] op_sel_hi:[1,0]
	v_pk_mul_f32 v[54:55], v[54:55], v[182:183] op_sel_hi:[1,0]
	v_pk_mul_f32 v[52:53], v[52:53], v[182:183] op_sel_hi:[1,0]
	v_pk_mul_f32 v[46:47], v[46:47], v[182:183] op_sel_hi:[1,0]
	v_pk_mul_f32 v[44:45], v[44:45], v[182:183] op_sel_hi:[1,0]
	v_pk_mul_f32 v[38:39], v[38:39], v[182:183] op_sel_hi:[1,0]
	v_pk_mul_f32 v[36:37], v[36:37], v[182:183] op_sel_hi:[1,0]
	v_max_f32_e32 v182, 0, v181
	v_exp_f32_e64 v184, -v182
	v_sub_f32_e32 v138, v138, v183
	v_sub_f32_e32 v139, v139, v183
	v_sub_f32_e32 v140, v140, v183
	v_sub_f32_e32 v141, v141, v183
	v_sub_f32_e32 v142, v142, v183
	v_sub_f32_e32 v143, v143, v183
	v_sub_f32_e32 v116, v116, v183
	v_sub_f32_e32 v117, v117, v183
	v_sub_f32_e32 v118, v118, v183
	v_sub_f32_e32 v119, v119, v183
	v_sub_f32_e32 v120, v120, v183
	v_sub_f32_e32 v121, v121, v183
	v_sub_f32_e32 v122, v122, v183
	v_sub_f32_e32 v123, v123, v183
	v_pk_add_f32 v[158:159], v[158:159], v[182:183]
	v_xor_b32_e32 v218, 0x80000000, v159
	v_xor_b32_e32 v222, 0x80000000, v158
	v_mov_b32_e32 v219, v218
	v_mov_b32_e32 v220, v218
	v_mov_b32_e32 v221, v218
	v_mov_b32_e32 v223, v222
	v_mov_b32_e32 v224, v222
	v_mov_b32_e32 v225, v222
	v_sub_f32_e32 v128, v128, v182
	v_sub_f32_e32 v129, v129, v182
	v_sub_f32_e32 v130, v130, v182
	v_sub_f32_e32 v131, v131, v182
	v_sub_f32_e32 v132, v132, v182
	v_sub_f32_e32 v133, v133, v182
	v_sub_f32_e32 v134, v134, v182
	v_sub_f32_e32 v135, v135, v182
	v_sub_f32_e32 v100, v100, v182
	v_sub_f32_e32 v101, v101, v182
	v_sub_f32_e32 v102, v102, v182
	v_sub_f32_e32 v103, v103, v182
	v_sub_f32_e32 v104, v104, v182
	v_sub_f32_e32 v105, v105, v182
	v_sub_f32_e32 v106, v106, v182
	v_sub_f32_e32 v107, v107, v182
	v_pk_mul_f32 v[66:67], v[66:67], v[184:185] op_sel_hi:[1,0]
	v_pk_mul_f32 v[64:65], v[64:65], v[184:185] op_sel_hi:[1,0]
	v_pk_mul_f32 v[58:59], v[58:59], v[184:185] op_sel_hi:[1,0]
	v_pk_mul_f32 v[56:57], v[56:57], v[184:185] op_sel_hi:[1,0]
	v_pk_mul_f32 v[50:51], v[50:51], v[184:185] op_sel_hi:[1,0]
	v_pk_mul_f32 v[48:49], v[48:49], v[184:185] op_sel_hi:[1,0]
	v_pk_mul_f32 v[42:43], v[42:43], v[184:185] op_sel_hi:[1,0]
	v_pk_mul_f32 v[40:41], v[40:41], v[184:185] op_sel_hi:[1,0]
	v_pk_mul_f32 v[34:35], v[34:35], v[184:185] op_sel_hi:[1,0]
	v_pk_mul_f32 v[32:33], v[32:33], v[184:185] op_sel_hi:[1,0]
